# group 0: scan pinned to 128 workgroups, the other 128 run all stage-1 items statically, meet at a 128-workgroup counter barrier and run the stage-2 items under the scan tail; stage1-to-stage2 grid bar
# speedup vs baseline: 1.0328x; 1.0074x over previous
.LBB0_3:
	s_or_b64 exec, exec, s[6:7]
	v_writelane_b32 v240, s3, 61
	v_writelane_b32 v240, 0, 63
	v_writelane_b32 v240, 0, 60
	v_writelane_b32 v240, 0, 59
	v_writelane_b32 v240, 0, 58
	s_load_dwordx16 s[16:31], s[0:1], 0x0
	v_mov_b32_e32 v2, v166
	s_cmp_lg_u32 s2, 0
	s_waitcnt lgkmcnt(0)
	v_writelane_b32 v245, s16, 0
	s_nop 1
	v_writelane_b32 v245, s17, 1
	v_writelane_b32 v245, s18, 2
	v_writelane_b32 v245, s19, 3
	v_writelane_b32 v245, s20, 4
	v_writelane_b32 v245, s21, 5
	v_writelane_b32 v245, s22, 6
	v_writelane_b32 v245, s23, 7
	v_writelane_b32 v245, s24, 8
	v_writelane_b32 v245, s25, 9
	v_writelane_b32 v245, s26, 10
	v_writelane_b32 v245, s27, 11
	v_writelane_b32 v245, s28, 12
	v_writelane_b32 v245, s29, 13
	v_writelane_b32 v245, s30, 14
	v_writelane_b32 v245, s31, 15
	s_cbranch_scc1 .LBB0_9
	v_ashrrev_i32_e32 v3, 31, v2
	v_lshl_add_u64 v[4:5], v[2:3], 2, s[92:93]
	v_add_co_u32_e32 v8, vcc, 0xb500000, v4
	v_mov_b32_e32 v6, 0
	s_nop 0
	v_addc_co_u32_e32 v9, vcc, 0, v5, vcc
	v_cmp_gt_i32_e32 vcc, 2, v2
	global_store_dword v[8:9], v6, off offset:256
	s_and_saveexec_b64 s[6:7], vcc
	s_cbranch_execz .LBB0_8
	s_load_dwordx16 s[16:31], s[0:1], 0x0
	v_lshlrev_b32_e32 v10, 8, v2
	v_ashrrev_i32_e32 v11, 31, v10
	s_mov_b64 s[8:9], 0
	v_mov_b32_e32 v7, v6
	s_waitcnt lgkmcnt(0)
	v_mov_b32_e32 v8, s26
	v_mov_b32_e32 v9, s27
	v_lshl_add_u64 v[8:9], v[10:11], 2, v[8:9]

.Lnc5_okf:
.Lnc5_done:
.LBB0_842:
	s_or_b64 exec, exec, s[0:1]
	v_readlane_b32 s26, v240, 27
	s_lshl_b32 s0, s26, 1
	v_readlane_b32 s1, v241, 30
	s_add_i32 s84, s0, s1
	s_lshl_b64 s[38:39], s[84:85], 2
	v_readlane_b32 s0, v243, 47
	s_add_u32 s24, s0, s38
	v_readlane_b32 s0, v243, 48
	s_addc_u32 s25, s0, s39
	s_cmp_eq_u32 s26, 0
	s_cselect_b64 s[78:79], -1, 0
	s_and_b64 s[0:1], s[78:79], exec
	s_cselect_b32 s64, 0x80, 0
	s_cselect_b32 s96, 32, 0
	s_cselect_b32 s97, 0, 0x800
	s_cmp_eq_u32 s94, 0x100
	s_cselect_b32 s96, s96, 8
	s_cselect_b32 s97, s97, 0
	s_or_b32 s65, s64, 0xa00
	s_barrier
	v_readlane_b32 s27, v240, 28
	s_branch .LBB0_845

.LBB0_845:
	s_cmp_ge_u32 s96, 32
	s_cbranch_scc0 .Lg0_no
	v_readlane_b32 s76, v241, 19
	s_nop 3
	s_and_b32 s0, s76, 7
	s_lshr_b32 s76, s76, 3
	s_cmp_lt_u32 s76, 16
	s_cbranch_scc0 .Lg0_ns
	s_cmp_eq_u32 s96, 32
	s_cbranch_scc0 .Lg0_exit
	s_lshl_b32 s0, s0, 4
	s_add_u32 s76, s76, s0
	s_mov_b32 s96, 62
	s_branch .Lg0_go
.Lg0_exit:
	s_mov_b64 s[0:1], -1
	s_branch .LBB0_844
.Lg0_ns:
	s_sub_u32 s76, s76, 16
	s_sub_u32 s1, s96, 32
	s_cmp_ge_u32 s1, 20
	s_cbranch_scc1 .Lg0_exit
	s_cmp_ge_u32 s1, 16
	s_cbranch_scc1 .Lg0_h
	s_cmp_ge_u32 s1, 4
	s_cbranch_scc1 .Lg0_d
	s_lshr_b32 s26, s1, 1
	s_lshl_b32 s26, s26, 3
	s_add_u32 s0, s0, s26
	s_lshl_b32 s0, s0, 5
	s_bitcmp1_b32 s1, 0
	s_cbranch_scc0 .Lg0_a
	s_sub_u32 s76, 31, s76
.Lg0_a:
	s_add_u32 s76, s76, s0
	s_add_u32 s76, s76, 0x80
	s_branch .Lg0_tail
.Lg0_d:
	s_sub_u32 s1, s1, 4
	s_lshr_b32 s26, s1, 1
	s_lshl_b32 s26, s26, 3
	s_add_u32 s0, s0, s26
	s_lshl_b32 s0, s0, 5
	s_and_b32 s1, s1, 1
	s_lshl_b32 s1, s1, 4
	s_add_u32 s76, s76, s1
	s_add_u32 s76, s76, s0
	s_add_u32 s76, s76, 0x280
	s_branch .Lg0_tail
.Lg0_h:
	s_sub_u32 s1, s1, 16
	s_lshl_b32 s1, s1, 7
	s_lshl_b32 s0, s0, 4
	s_add_u32 s76, s76, s0
	s_add_u32 s76, s76, s1
	s_add_u32 s76, s76, 0x880

.LBB0_948:
	s_waitcnt vmcnt(0)
	s_waitcnt lgkmcnt(0)
	s_barrier
	s_and_saveexec_b64 s[0:1], s[74:75]
	s_cbranch_execz .LBB0_1001
	s_cmp_ge_u32 s96, 32
	s_cbranch_scc0 .Lpb_normal
	v_readlane_b32 s24, v241, 19
	v_readlane_b32 s26, v240, 58
	s_nop 3
	s_lshr_b32 s24, s24, 3
	s_cmp_lt_u32 s24, 16
	s_cbranch_scc1 .LBB0_1001
	s_waitcnt vmcnt(0) lgkmcnt(0)
	buffer_wbl2 sc1
	s_waitcnt vmcnt(0)
	s_add_u32 s24, s92, 0xb500a00
	s_addc_u32 s25, s93, 0
	s_add_u32 s26, s26, 1
	s_nop 1
	v_writelane_b32 v240, s26, 58
	s_lshl_b32 s26, s26, 7
	v_mov_b32_e32 v0, 0
	v_mov_b32_e32 v1, 1
	global_atomic_add v0, v1, s[24:25]
	s_waitcnt vmcnt(0)
.Lpb_poll:
	global_load_dword v2, v0, s[24:25] sc0 sc1
	s_waitcnt vmcnt(0)
	v_cmp_gt_u32_e32 vcc, s26, v2
	s_cbranch_vccz .Lpb_ok
	s_sleep 2
	s_branch .Lpb_poll
.Lpb_ok:
	buffer_inv sc1
	s_waitcnt vmcnt(0)
	s_branch .LBB0_1001
.Lpb_normal:
	s_waitcnt vmcnt(0) lgkmcnt(0)
	v_readlane_b32 s26, v240, 63
	v_readlane_b32 s27, v240, 61
	v_readlane_b32 s28, v240, 62
	s_add_u32 s24, s92, 0xb500900
	s_addc_u32 s25, s93, 0
	s_add_i32 s26, s26, 1
	s_nop 1
	v_writelane_b32 v240, s26, 63
	v_mov_b32_e32 v0, s27
	v_lshlrev_b32_e32 v0, 7, v0
	v_lshl_add_u32 v0, s28, 2, v0
	v_add_u32_e32 v0, 0x1400, v0
	v_mov_b32_e32 v1, s26
	global_store_dword v0, v1, s[24:25]
	s_cmp_lg_u32 s28, 0
	s_cbranch_scc1 .Lnc6_f
	buffer_inv sc1
	v_readlane_b32 s29, v240, 60
	s_mov_b32 exec_lo, -1
	s_mov_b32 exec_hi, 0
	v_mbcnt_lo_u32_b32 v2, -1, 0
	s_cmp_lg_u32 s29, 0
	s_cbranch_scc1 .Lnc6_have
	v_lshlrev_b32_e32 v3, 8, v2
	v_add_u32_e32 v3, 0x400, v3
	global_load_dword v4, v3, s[24:25] sc0 sc1
	s_waitcnt vmcnt(0)
	v_readlane_b32 s29, v4, s27
	v_cmp_ne_u32_e32 vcc, 0, v4
	s_nop 3
	s_and_b32 s28, vcc_lo, 0xffff
	v_writelane_b32 v240, s29, 60
	v_writelane_b32 v240, s28, 59

.Lnc6_okf:
.Lnc6_done:
.LBB0_1001:
	s_or_b64 exec, exec, s[0:1]
	s_add_u32 s0, s92, s38
	s_addc_u32 s1, s93, s39
	s_add_u32 s24, s0, 0xb500104
	s_addc_u32 s25, s1, 0
	s_cmp_eq_u32 s94, 0x100
	s_cselect_b32 s97, 0, 4
	s_cmp_ge_u32 s96, 32
	s_cselect_b32 s97, 16, s97
	s_barrier
	s_branch .LBB0_1004

.LBB0_1004:
	s_cmp_ge_u32 s97, 16
	s_cbranch_scc0 .Lg2_no
	v_readlane_b32 s26, v241, 19
	s_nop 3
	s_and_b32 s0, s26, 7
	s_lshr_b32 s26, s26, 3
	s_cmp_lt_u32 s26, 16
	s_cbranch_scc1 .Lg2_exit
	s_sub_u32 s26, s26, 16
	s_sub_u32 s1, s97, 16
	s_cmp_ge_u32 s1, 6
	s_cbranch_scc1 .Lg2_exit
	s_cmp_ge_u32 s1, 4
	s_cbranch_scc1 .Lg2_c
	s_lshr_b32 s27, s1, 1
	s_lshl_b32 s27, s27, 3
	s_add_u32 s0, s0, s27
	s_lshl_b32 s0, s0, 5
	s_bitcmp1_b32 s1, 0
	s_cbranch_scc0 .Lg2_a
	s_sub_u32 s26, 31, s26
.Lg2_a:
	s_add_u32 s26, s26, s0
	s_branch .Lg2_tail
.Lg2_c:
	s_sub_u32 s1, s1, 4
	s_lshl_b32 s1, s1, 7
	s_lshl_b32 s0, s0, 4
	s_add_u32 s26, s26, s0
	s_add_u32 s26, s26, s1
	s_add_u32 s26, s26, 0x200

.LBB0_1059:
	s_andn2_b64 vcc, exec, s[78:79]
	s_cbranch_vccnz .LBB0_1117
	s_waitcnt vmcnt(0)
	s_barrier
	s_and_saveexec_b64 s[0:1], s[74:75]
	v_readlane_b32 s2, v241, 19
	s_cbranch_execz .LBB0_1113
	s_waitcnt vmcnt(0) lgkmcnt(0)
	v_readlane_b32 s26, v240, 63
	v_readlane_b32 s27, v240, 61
	v_readlane_b32 s28, v240, 62
	s_add_u32 s24, s92, 0xb500900
	s_addc_u32 s25, s93, 0
	s_add_i32 s26, s26, 1
	s_nop 1
	v_writelane_b32 v240, s26, 63
	v_mov_b32_e32 v0, s27
	v_lshlrev_b32_e32 v0, 7, v0
	v_lshl_add_u32 v0, s28, 2, v0
	v_add_u32_e32 v0, 0x1400, v0
	v_mov_b32_e32 v1, s26
	global_store_dword v0, v1, s[24:25]
	s_cmp_lg_u32 s28, 0
	s_cbranch_scc1 .Lnc7_f
	buffer_inv sc1
	v_readlane_b32 s29, v240, 60
	s_mov_b32 exec_lo, -1
	s_mov_b32 exec_hi, 0
	v_mbcnt_lo_u32_b32 v2, -1, 0
	s_cmp_lg_u32 s29, 0
	s_cbranch_scc1 .Lnc7_have
	v_lshlrev_b32_e32 v3, 8, v2
	v_add_u32_e32 v3, 0x400, v3
	global_load_dword v4, v3, s[24:25] sc0 sc1
	s_waitcnt vmcnt(0)
	v_readlane_b32 s29, v4, s27
	v_cmp_ne_u32_e32 vcc, 0, v4
	s_nop 3
	s_and_b32 s28, vcc_lo, 0xffff
	v_writelane_b32 v240, s29, 60
	v_writelane_b32 v240, s28, 59
